# attention phase: one static s_setprio 1 for the younger wave half (waves 4-7), reset at phase end; on top of the fast-path kernel
# speedup vs baseline: 1.0135x; 1.0100x over previous
; #define LAS __attribute__((address_space(3)))
; __device__ __forceinline__ void phase_B1(CArgs& a, int l, unsigned char* lds, const int tid, const int bx, const int G) {
;     {
;         for (int vc = bx; vc < 256; vc += G) {
;             const int vcu = (G == 256) ? ((vc & 7) * 32 + (vc >> 3)) : vc;
;             const int combo = vcu >> 2, s = vcu & 3;
;             const int b = combo >> 3, h = (combo >> 1) & 3, mp = combo & 1;
;             for (int i = 0; i < 4; ++i) { const int qb = (i == 0) ? s : (i == 1) ? 7 - s : (i == 2) ? 8 + s : 15 - s; fa3::unit(a.ws, (LAS unsigned char*)lds, b, h, mp, qb, tid); }
; __global__ void __launch_bounds__(NTHR, 2) mk_fwd(Args a_by_value) {
;     ...
;         else if (p == 2) { PHASE_ENTER(2); phase_B1(a, l, lds, tid, bx, G); }
.LBB0_165:
	s_and_b64 vcc, exec, s[4:5]
	s_cbranch_vccz .LBB0_215
	s_mov_b32 s4, s2
	s_waitcnt lgkmcnt(0)
	s_mov_b64 s[8:9], s[0:1]
	s_mov_b32 s5, s46
	s_mov_b32 s6, s37
	s_mov_b32 s7, s3
	v_mbcnt_lo_u32_b32 v164, -1, 0
	v_mbcnt_hi_u32_b32 v164, -1, v164
	v_lshl_or_b32 v164, s7, 6, v164
	s_cmp_ge_u32 s3, 4
	s_cbranch_scc0 .Lp2_prio_done
	s_setprio 1
.Lp2_prio_done:
	s_load_dwordx2 s[8:9], s[8:9], 0xb0
	s_cmpk_gt_i32 s4, 0xff
	s_cbranch_scc1 .LBB0_212
	s_cmpk_eq_i32 s6, 0x100
	s_cselect_b64 s[12:13], -1, 0
	s_waitcnt lgkmcnt(0)
	s_add_u32 s5, s8, 0x6600000
	s_addc_u32 s7, s9, 0
	s_add_u32 s10, s8, 0x8600000
	s_addc_u32 s11, s9, 0
	s_add_u32 s28, s8, 0xa600000
	s_addc_u32 s36, s9, 0
	s_add_u32 s42, s8, 0x2600000
	s_addc_u32 s43, s9, 0
	s_add_u32 s44, s8, 0x8630000
	s_addc_u32 s45, s9, 0
	s_mov_b32 s62, s4
	s_branch .LBB0_169

; __global__ void __launch_bounds__(NTHR, 2) mk_fwd(Args a_by_value) {
;     ...
;         if (ph + 1 < ph_hi) cg::this_grid().sync();
.LBB0_530:
	s_setprio 0
	s_waitcnt vmcnt(0) lgkmcnt(0)
	s_barrier
	s_mov_b64 s[4:5], exec
	v_readlane_b32 s6, v255, 4
	v_readlane_b32 s7, v255, 5
	s_and_b64 s[6:7], s[4:5], s[6:7]
	s_mov_b64 exec, s[6:7]
	s_cbranch_execz .LBB0_3
	s_cmp_lg_u32 s101, 0
	s_cbranch_scc1 .Lfb_fast
	s_mov_b32 s101, 1
	v_readlane_b32 s6, v255, 0
	v_readlane_b32 s7, v255, 1
	buffer_wbl2 sc1
	s_load_dwordx2 s[6:7], s[6:7], 0x58
	s_mov_b64 s[8:9], exec
	v_mbcnt_lo_u32_b32 v2, s8, 0
	v_mbcnt_hi_u32_b32 v2, s9, v2
	v_cmp_eq_u32_e32 vcc, 0, v2
	s_waitcnt lgkmcnt(0)
	global_load_dword v0, v1, s[6:7] offset:40
	s_and_saveexec_b64 s[12:13], vcc
	s_cbranch_execz .LBB0_533
	s_bcnt1_i32_b64 s8, s[8:9]
	v_mov_b32_e32 v3, s8
	global_atomic_add v3, v1, v3, s[6:7] offset:32 sc0
